# on top of v36: 10 of 16 F1 running-mix quads on-chip (7th VGPR quad in v204-207 freed by scalar has_next compares, third 8 KiB LDS slot; static LDS 24 KiB)
# speedup vs baseline: 1.0071x; 1.0056x over previous
.LBB0_870:
	s_add_i32 s46, s46, 1
	s_lshr_b32 s4, s46, 2
	s_mul_hi_i32 s5, s4, s1
	s_mul_i32 s4, s4, s1
	s_add_u32 s26, s4, s28
	s_addc_u32 s27, s5, s43
	s_cmp_gt_u32 s26, 0x1ff
	s_cselect_b32 s4, 1, 0
	s_cmp_lg_u32 s27, 0
	s_cselect_b32 s4, 1, s4
	s_cmp_lg_u32 s4, 0
	s_cselect_b64 vcc, exec, 0
	s_cselect_b64 s[4:5], 0, exec
	s_cbranch_vccnz .LBB0_876
	s_ashr_i32 s16, s26, 31
	s_lshr_b32 s16, s16, 29
	s_add_i32 s18, s26, s16
	s_and_b32 s16, s18, -8
	s_sub_i32 s20, s26, s16
	s_cmp_gt_i32 s20, -1
	s_mov_b64 s[16:17], -1
	s_cbranch_scc0 .LBB0_873
	s_lshl_b32 s19, s20, 6
	s_mov_b64 s[16:17], 0

.LBB0_926:
	s_nop 0
	global_load_dwordx4 v[72:75], v[72:73], off offset:256
	s_and_b64 vcc, exec, s[6:7]
	s_cbranch_vccnz .LBB0_928
	ds_read_b128 v[64:67], v252 offset:16384

.LBB0_940:
	v_cvt_pk_bf16_f32 v20, v20, v21
	v_cvt_pk_bf16_f32 v21, v22, v23
	v_cvt_pk_bf16_f32 v22, v16, v17
	s_waitcnt vmcnt(6)
	v_lshlrev_b32_e32 v16, 16, v76
	v_and_b32_e32 v17, 0xffff0000, v76
	v_pk_mul_f32 v[12:13], v[12:13], v[16:17]
	v_lshlrev_b32_e32 v16, 16, v77
	v_and_b32_e32 v17, 0xffff0000, v77
	v_pk_mul_f32 v[14:15], v[14:15], v[16:17]
	v_lshlrev_b32_e32 v16, 16, v78
	v_and_b32_e32 v17, 0xffff0000, v78
	v_pk_mul_f32 v[8:9], v[8:9], v[16:17]
	v_lshlrev_b32_e32 v16, 16, v79
	v_and_b32_e32 v17, 0xffff0000, v79
	v_cvt_pk_bf16_f32 v23, v18, v19
	s_and_b64 vcc, exec, s[6:7]
	v_pk_mul_f32 v[10:11], v[10:11], v[16:17]
	global_store_dwordx4 v[24:25], v[20:23], off offset:256
	s_cbranch_vccnz .LBB0_942
	v_lshlrev_b32_e32 v16, 16, v204
	v_and_b32_e32 v17, 0xffff0000, v204
	v_lshlrev_b32_e32 v18, 16, v205
	v_and_b32_e32 v19, 0xffff0000, v205
	v_lshlrev_b32_e32 v20, 16, v206
	v_and_b32_e32 v21, 0xffff0000, v206
	v_lshlrev_b32_e32 v22, 16, v207
	v_and_b32_e32 v23, 0xffff0000, v207
	v_pk_add_f32 v[14:15], v[14:15], v[18:19]
	v_pk_add_f32 v[12:13], v[12:13], v[16:17]
	v_pk_add_f32 v[10:11], v[10:11], v[22:23]
	v_pk_add_f32 v[8:9], v[8:9], v[20:21]
.LBB0_942:
	v_add_u32_e32 v16, 0xb0, v210
	v_cvt_pk_bf16_f32 v12, v12, v13
	v_cvt_pk_bf16_f32 v13, v14, v15
	v_cvt_pk_bf16_f32 v15, v10, v11
	s_waitcnt vmcnt(6)
	s_waitcnt lgkmcnt(0)
	v_lshlrev_b32_e32 v10, 16, v72
	v_and_b32_e32 v11, 0xffff0000, v72
	v_ashrrev_i32_e32 v17, 31, v16
	v_pk_mul_f32 v[4:5], v[4:5], v[10:11]
	v_lshlrev_b32_e32 v10, 16, v73
	v_and_b32_e32 v11, 0xffff0000, v73
	v_cvt_pk_bf16_f32 v14, v8, v9
	v_lshlrev_b64 v[8:9], 12, v[16:17]
	v_pk_mul_f32 v[6:7], v[6:7], v[10:11]
	v_lshlrev_b32_e32 v10, 16, v74
	v_and_b32_e32 v11, 0xffff0000, v74
	v_lshl_add_u64 v[8:9], s[10:11], 0, v[8:9]
	v_pk_mul_f32 v[0:1], v[0:1], v[10:11]
	v_lshlrev_b32_e32 v10, 16, v75
	v_and_b32_e32 v11, 0xffff0000, v75
	v_lshl_add_u64 v[8:9], v[208:209], 1, v[8:9]
	s_and_b64 vcc, exec, s[6:7]
	v_pk_mul_f32 v[2:3], v[2:3], v[10:11]
	v_mov_b32_e32 v204, v12
	v_mov_b32_e32 v205, v13
	v_mov_b32_e32 v206, v14
	v_mov_b32_e32 v207, v15
	s_cmp_eq_u32 s98, 3
	s_cbranch_scc0 .Lf1k_302
	global_store_dwordx4 v[8:9], v[12:15], off
.Lf1k_302:
	s_cbranch_vccnz .LBB0_944
	v_lshlrev_b32_e32 v10, 16, v64
	v_and_b32_e32 v11, 0xffff0000, v64
	v_lshlrev_b32_e32 v12, 16, v65
	v_and_b32_e32 v13, 0xffff0000, v65
	v_lshlrev_b32_e32 v14, 16, v66
	v_and_b32_e32 v15, 0xffff0000, v66
	v_lshlrev_b32_e32 v16, 16, v67
	v_and_b32_e32 v17, 0xffff0000, v67
	v_pk_add_f32 v[6:7], v[6:7], v[12:13]
	v_pk_add_f32 v[4:5], v[4:5], v[10:11]
	v_pk_add_f32 v[2:3], v[2:3], v[16:17]
	v_pk_add_f32 v[0:1], v[0:1], v[14:15]
.LBB0_944:
	v_cvt_pk_bf16_f32 v4, v4, v5
	v_cvt_pk_bf16_f32 v5, v6, v7
	v_cvt_pk_bf16_f32 v6, v0, v1
	v_cvt_pk_bf16_f32 v7, v2, v3
	ds_write_b128 v252, v[4:7] offset:16384
	s_cmp_eq_u32 s98, 3
	s_cbranch_scc0 .Lf1k_303
	global_store_dwordx4 v[8:9], v[4:7], off offset:256
.Lf1k_303:
	s_andn2_b64 vcc, exec, s[4:5]
	s_mov_b64 s[4:5], -1
	s_cbranch_vccnz .LBB0_869
	s_andn2_b64 vcc, exec, s[8:9]
	s_cbranch_vccnz .LBB0_868
	s_barrier
	s_branch .LBB0_868

	.amdhsa_kernel _Z6mk_fwd4Args
		.amdhsa_group_segment_fixed_size 24576
		.amdhsa_private_segment_fixed_size 0
		.amdhsa_kernarg_size 448
		.amdhsa_user_sgpr_count 2
		.amdhsa_user_sgpr_dispatch_ptr 0
		.amdhsa_user_sgpr_queue_ptr 0
		.amdhsa_user_sgpr_kernarg_segment_ptr 1
		.amdhsa_user_sgpr_dispatch_id 0
		.amdhsa_user_sgpr_kernarg_preload_length 0
		.amdhsa_user_sgpr_kernarg_preload_offset 0
		.amdhsa_user_sgpr_private_segment_size 0
		.amdhsa_uses_dynamic_stack 0
		.amdhsa_enable_private_segment 0
		.amdhsa_system_sgpr_workgroup_id_x 1
		.amdhsa_system_sgpr_workgroup_id_y 0
		.amdhsa_system_sgpr_workgroup_id_z 0
		.amdhsa_system_sgpr_workgroup_info 0
		.amdhsa_system_vgpr_workitem_id 2
		.amdhsa_next_free_vgpr 256
		.amdhsa_next_free_sgpr 102
		.amdhsa_accum_offset 256
		.amdhsa_reserve_vcc 1
		.amdhsa_float_round_mode_32 0
		.amdhsa_float_round_mode_16_64 0
		.amdhsa_float_denorm_mode_32 3
		.amdhsa_float_denorm_mode_16_64 3
		.amdhsa_dx10_clamp 1
		.amdhsa_ieee_mode 1
		.amdhsa_fp16_overflow 0
		.amdhsa_tg_split 0
		.amdhsa_exception_fp_ieee_invalid_op 0
		.amdhsa_exception_fp_denorm_src 0
		.amdhsa_exception_fp_ieee_div_zero 0
		.amdhsa_exception_fp_ieee_overflow 0
		.amdhsa_exception_fp_ieee_underflow 0
		.amdhsa_exception_fp_ieee_inexact 0
		.amdhsa_exception_int_div_zero 0
	.end_amdhsa_kernel

amdhsa.kernels:
  - .agpr_count:     0
    .args:
      - .offset:         0
        .size:           192
        .value_kind:     by_value
      - .offset:         192
        .size:           4
        .value_kind:     hidden_block_count_x
      - .offset:         196
        .size:           4
        .value_kind:     hidden_block_count_y
      - .offset:         200
        .size:           4
        .value_kind:     hidden_block_count_z
      - .offset:         204
        .size:           2
        .value_kind:     hidden_group_size_x
      - .offset:         206
        .size:           2
        .value_kind:     hidden_group_size_y
      - .offset:         208
        .size:           2
        .value_kind:     hidden_group_size_z
      - .offset:         210
        .size:           2
        .value_kind:     hidden_remainder_x
      - .offset:         212
        .size:           2
        .value_kind:     hidden_remainder_y
      - .offset:         214
        .size:           2
        .value_kind:     hidden_remainder_z
      - .offset:         232
        .size:           8
        .value_kind:     hidden_global_offset_x
      - .offset:         240
        .size:           8
        .value_kind:     hidden_global_offset_y
      - .offset:         248
        .size:           8
        .value_kind:     hidden_global_offset_z
      - .offset:         256
        .size:           2
        .value_kind:     hidden_grid_dims
      - .offset:         280
        .size:           8
        .value_kind:     hidden_multigrid_sync_arg
      - .offset:         312
        .size:           4
        .value_kind:     hidden_dynamic_lds_size
    .group_segment_fixed_size: 24576
    .kernarg_segment_align: 8
    .kernarg_segment_size: 448
    .language:       OpenCL C
    .language_version:
      - 2
      - 0
    .max_flat_workgroup_size: 512
    .name:           _Z6mk_fwd4Args
    .private_segment_fixed_size: 0
    .sgpr_count:     108
    .sgpr_spill_count: 37
    .symbol:         _Z6mk_fwd4Args.kd
    .uniform_work_group_size: 1
    .uses_dynamic_stack: false
    .vgpr_count:     256
    .vgpr_spill_count: 0
    .wavefront_size: 64
